# RG-LRU walk: depthwise-conv block rewritten by hand as plain FMA chains with all LDS reads up front (was SLP-packed v_pk_mul with v_mov shuffles)
# speedup vs baseline: 1.0164x; 1.0051x over previous
.LBB0_537:
	s_or_b64 exec, exec, s[16:17]
	s_xor_b32 s16, s34, 1
	s_mul_i32 s17, s16, 0x4300
	v_add_u32_e32 v1, s17, v107
	ds_read_b128 v[64:67], v1
	ds_read_b128 v[68:71], v1 offset:256
	ds_read_b128 v[84:87], v1 offset:512
	ds_read_b128 v[92:95], v1 offset:768
	ds_read_b128 v[60:63], v1 offset:1024
	ds_read_b128 v[96:99], v120
	ds_read_b128 v[100:103], v120 offset:16
	ds_read_b128 v[142:145], v120 offset:512
	ds_read_b128 v[164:167], v120 offset:528
	ds_read_b128 v[168:171], v120 offset:1024
	ds_read_b128 v[204:207], v120 offset:1040
	ds_read_b128 v[172:175], v120 offset:1536
	ds_read_b128 v[192:195], v120 offset:1552
	ds_read_b128 v[196:199], v120 offset:2048
	ds_read_b128 v[200:203], v120 offset:2064
	s_mulk_i32 s16, 0x4400
	v_add_u32_e32 v2, s16, v112
	s_mul_i32 s16, s34, 0x4400
	v_cndmask_b32_e64 v131, v131, v135, s[6:7]
	s_add_i32 s69, s69, 1
	s_add_i32 s19, s19, 0xfff90000
	s_sub_i32 s68, s68, 64
	s_waitcnt lgkmcnt(0)
	v_lshlrev_b32_e32 v208, 16, v64
	v_and_b32_e32 v209, 0xffff0000, v64
	v_lshlrev_b32_e32 v210, 16, v68
	v_and_b32_e32 v211, 0xffff0000, v68
	v_lshlrev_b32_e32 v212, 16, v84
	v_and_b32_e32 v213, 0xffff0000, v84
	v_lshlrev_b32_e32 v214, 16, v92
	v_and_b32_e32 v215, 0xffff0000, v92
	v_lshlrev_b32_e32 v216, 16, v60
	v_and_b32_e32 v217, 0xffff0000, v60
	v_fma_f32 v218, v96, v208, v196
	v_fmac_f32_e32 v218, v142, v210
	v_fmac_f32_e32 v218, v168, v212
	v_fmac_f32_e32 v218, v172, v214
	v_fma_f32 v226, v96, v210, v196
	v_fmac_f32_e32 v226, v142, v212
	v_fmac_f32_e32 v226, v168, v214
	v_fmac_f32_e32 v226, v172, v216
	v_fma_f32 v219, v97, v209, v197
	v_fmac_f32_e32 v219, v143, v211
	v_fmac_f32_e32 v219, v169, v213
	v_fmac_f32_e32 v219, v173, v215
	v_fma_f32 v227, v97, v211, v197
	v_fmac_f32_e32 v227, v143, v213
	v_fmac_f32_e32 v227, v169, v215
	v_fmac_f32_e32 v227, v173, v217
	v_lshlrev_b32_e32 v208, 16, v65
	v_and_b32_e32 v209, 0xffff0000, v65
	v_lshlrev_b32_e32 v210, 16, v69
	v_and_b32_e32 v211, 0xffff0000, v69
	v_lshlrev_b32_e32 v212, 16, v85
	v_and_b32_e32 v213, 0xffff0000, v85
	v_lshlrev_b32_e32 v214, 16, v93
	v_and_b32_e32 v215, 0xffff0000, v93
	v_lshlrev_b32_e32 v216, 16, v61
	v_and_b32_e32 v217, 0xffff0000, v61
	v_fma_f32 v220, v98, v208, v198
	v_fmac_f32_e32 v220, v144, v210
	v_fmac_f32_e32 v220, v170, v212
	v_fmac_f32_e32 v220, v174, v214
	v_fma_f32 v228, v98, v210, v198
	v_fmac_f32_e32 v228, v144, v212
	v_fmac_f32_e32 v228, v170, v214
	v_fmac_f32_e32 v228, v174, v216
	v_fma_f32 v221, v99, v209, v199
	v_fmac_f32_e32 v221, v145, v211
	v_fmac_f32_e32 v221, v171, v213
	v_fmac_f32_e32 v221, v175, v215
	v_fma_f32 v229, v99, v211, v199
	v_fmac_f32_e32 v229, v145, v213
	v_fmac_f32_e32 v229, v171, v215
	v_fmac_f32_e32 v229, v175, v217
	v_lshlrev_b32_e32 v208, 16, v66
	v_and_b32_e32 v209, 0xffff0000, v66
	v_lshlrev_b32_e32 v210, 16, v70
	v_and_b32_e32 v211, 0xffff0000, v70
	v_lshlrev_b32_e32 v212, 16, v86
	v_and_b32_e32 v213, 0xffff0000, v86
	v_lshlrev_b32_e32 v214, 16, v94
	v_and_b32_e32 v215, 0xffff0000, v94
	v_lshlrev_b32_e32 v216, 16, v62
	v_and_b32_e32 v217, 0xffff0000, v62
	v_fma_f32 v222, v100, v208, v200
	v_fmac_f32_e32 v222, v164, v210
	v_fmac_f32_e32 v222, v204, v212
	v_fmac_f32_e32 v222, v192, v214
	v_fma_f32 v230, v100, v210, v200
	v_fmac_f32_e32 v230, v164, v212
	v_fmac_f32_e32 v230, v204, v214
	v_fmac_f32_e32 v230, v192, v216
	v_fma_f32 v223, v101, v209, v201
	v_fmac_f32_e32 v223, v165, v211
	v_fmac_f32_e32 v223, v205, v213
	v_fmac_f32_e32 v223, v193, v215
	v_fma_f32 v231, v101, v211, v201
	v_fmac_f32_e32 v231, v165, v213
	v_fmac_f32_e32 v231, v205, v215
	v_fmac_f32_e32 v231, v193, v217
	v_lshlrev_b32_e32 v208, 16, v67
	v_and_b32_e32 v209, 0xffff0000, v67
	v_lshlrev_b32_e32 v210, 16, v71
	v_and_b32_e32 v211, 0xffff0000, v71
	v_lshlrev_b32_e32 v212, 16, v87
	v_and_b32_e32 v213, 0xffff0000, v87
	v_lshlrev_b32_e32 v214, 16, v95
	v_and_b32_e32 v215, 0xffff0000, v95
	v_lshlrev_b32_e32 v216, 16, v63
	v_and_b32_e32 v217, 0xffff0000, v63
	v_fma_f32 v224, v102, v208, v202
	v_fmac_f32_e32 v224, v166, v210
	v_fmac_f32_e32 v224, v206, v212
	v_fmac_f32_e32 v224, v194, v214
	v_fma_f32 v232, v102, v210, v202
	v_fmac_f32_e32 v232, v166, v212
	v_fmac_f32_e32 v232, v206, v214
	v_fmac_f32_e32 v232, v194, v216
	v_fma_f32 v225, v103, v209, v203
	v_fmac_f32_e32 v225, v167, v211
	v_fmac_f32_e32 v225, v207, v213
	v_fmac_f32_e32 v225, v195, v215
	v_fma_f32 v233, v103, v211, v203
	v_fmac_f32_e32 v233, v167, v213
	v_fmac_f32_e32 v233, v207, v215
	v_fmac_f32_e32 v233, v195, v217
	v_cvt_pk_bf16_f32 v234, v218, v219
	v_cvt_pk_bf16_f32 v235, v220, v221
	v_cvt_pk_bf16_f32 v236, v222, v223
	v_cvt_pk_bf16_f32 v237, v224, v225
	v_cvt_pk_bf16_f32 v238, v226, v227
	v_cvt_pk_bf16_f32 v239, v228, v229
	v_cvt_pk_bf16_f32 v240, v230, v231
	v_cvt_pk_bf16_f32 v241, v232, v233
	ds_write_b128 v2, v[234:237] offset:34304
	ds_write_b128 v2, v[238:241] offset:34576
	v_add_u32_e32 v1, s16, v127
	ds_read_b128 v[60:63], v1 offset:34304
	ds_read_b128 v[64:67], v1 offset:34368
	ds_read_b128 v[84:87], v1 offset:38656
	ds_read_b128 v[92:95], v1 offset:38720
	ds_read_b128 v[100:103], v1 offset:43008
	ds_read_b128 v[142:145], v1 offset:43072
	ds_read_b128 v[168:171], v1 offset:47360
	ds_read_b128 v[172:175], v1 offset:47424
	s_waitcnt lgkmcnt(0)
; #define LAS __attribute__((address_space(3)))
; __device__ __forceinline__ float bf_1(bf16_t h) { return __uint_as_float(((unsigned)h) << 16); }
; template <int DIR>
; __device__ __forceinline__ void rnn_item(LAS unsigned char* lds, const bf16_t* proj, bf16_t* hout, int hpitch, int layer, int s, int n) {
;     ...
; #pragma unroll
;         for (int ks = 0; ks < 4; ++ks)
; #pragma unroll
;             for (int mt = 0; mt < 4; ++mt) {
;                 const bf16x8 af = *(const LAS bf16x8*)(At + buf * 17408 + (mt * 16 + l16) * 272 + ks * 64 + kg * 16);
;                 aA[mt] = __builtin_amdgcn_mfma_f32_16x16x32_bf16(af, bfr[0][ks], aA[mt], 0, 0, 0);
;                 aX[mt] = __builtin_amdgcn_mfma_f32_16x16x32_bf16(af, bfr[1][ks], aX[mt], 0, 0, 0);
;             }
;         {   typedef float f32x2 __attribute__((ext_vector_type(2)));
; #pragma unroll
;             for (int mt = 0; mt < 4; ++mt)
; #pragma unroll
;                 for (int rp = 0; rp < 2; ++rp) {
;                     const LAS unsigned char* xp = At + buf * 17408 + (mt * 16 + kg * 4 + 2 * rp) * 272 + (w * 16 + l16) * 2;
;                     const f32x2 xc = {bf_1(*(const LAS bf16_t*)xp), bf_1(*(const LAS bf16_t*)(xp + 272))};
;                     const f32x2 xa = {aA[mt][2 * rp], aA[mt][2 * rp + 1]}, xx = {aX[mt][2 * rp], aX[mt][2 * rp + 1]};
;                     f32x2 ta = xa * (-LOG2E) + nba, tx = xx * (-LOG2E) + nbx;
;                     ta.x = fminf(ta.x, 60.f); ta.y = fminf(ta.y, 60.f); tx.x = fminf(tx.x, 60.f); tx.y = fminf(tx.y, 60.f);
;                     f32x2 ea, ex; ea.x = __builtin_amdgcn_exp2f(ta.x); ea.y = __builtin_amdgcn_exp2f(ta.y); ex.x = __builtin_amdgcn_exp2f(tx.x); ex.y = __builtin_amdgcn_exp2f(tx.y);
;                     const f32x2 da = ea + 1.0f, dx = ex + 1.0f, dd = da * dx;
;                     f32x2 inv; inv.x = __builtin_amdgcn_rcpf(dd.x); inv.y = __builtin_amdgcn_rcpf(dd.y);
;                     const f32x2 rr = dx * inv, ii = da * inv, tt = rr * clam2;
;                     f32x2 av; av.x = __builtin_amdgcn_exp2f(tt.x); av.y = __builtin_amdgcn_exp2f(tt.y);
;                     f32x2 om = 1.0f - av * av; om.x = fmaxf(om.x, 0.f); om.y = fmaxf(om.y, 0.f);
;                     f32x2 sq; sq.x = __builtin_amdgcn_sqrtf(om.x); sq.y = __builtin_amdgcn_sqrtf(om.y);
;                     const f32x2 bv = sq * (ii * xc);
	v_mfma_f32_16x16x32_bf16 v[68:71], v[60:63], v[4:7], 0
	v_mfma_f32_16x16x32_bf16 v[60:63], v[60:63], v[20:23], 0
	v_mfma_f32_16x16x32_bf16 v[96:99], v[84:87], v[4:7], 0
	v_mfma_f32_16x16x32_bf16 v[84:87], v[84:87], v[20:23], 0
	v_mfma_f32_16x16x32_bf16 v[164:167], v[100:103], v[4:7], 0
	v_mfma_f32_16x16x32_bf16 v[100:103], v[100:103], v[20:23], 0
	v_mfma_f32_16x16x32_bf16 v[192:195], v[168:171], v[4:7], 0
	v_mfma_f32_16x16x32_bf16 v[168:171], v[168:171], v[20:23], 0
	v_mfma_f32_16x16x32_bf16 v[68:71], v[64:67], v[8:11], v[68:71]
	v_mfma_f32_16x16x32_bf16 v[60:63], v[64:67], v[24:27], v[60:63]
	v_mfma_f32_16x16x32_bf16 v[64:67], v[92:95], v[8:11], v[96:99]
	v_mfma_f32_16x16x32_bf16 v[84:87], v[92:95], v[24:27], v[84:87]
	v_mfma_f32_16x16x32_bf16 v[92:95], v[142:145], v[8:11], v[164:167]
	v_mfma_f32_16x16x32_bf16 v[96:99], v[142:145], v[24:27], v[100:103]
	v_mfma_f32_16x16x32_bf16 v[142:145], v[172:175], v[24:27], v[168:171]
	s_nop 0
	ds_read_b128 v[164:167], v1 offset:34432
	s_nop 0
	ds_read_b128 v[168:171], v1 offset:34496
	v_mfma_f32_16x16x32_bf16 v[100:103], v[172:175], v[8:11], v[192:195]
	s_waitcnt lgkmcnt(0)
	v_mfma_f32_16x16x32_bf16 v[68:71], v[164:167], v[12:15], v[68:71]
	v_mfma_f32_16x16x32_bf16 v[60:63], v[164:167], v[28:31], v[60:63]
	ds_read_b128 v[164:167], v1 offset:38784
	ds_read_b128 v[172:175], v1 offset:38848
	s_waitcnt lgkmcnt(0)
	v_mfma_f32_16x16x32_bf16 v[64:67], v[164:167], v[12:15], v[64:67]
	v_mfma_f32_16x16x32_bf16 v[84:87], v[164:167], v[28:31], v[84:87]
	ds_read_b128 v[164:167], v1 offset:43136
	ds_read_b128 v[192:195], v1 offset:43200
	s_waitcnt lgkmcnt(0)
	v_mfma_f32_16x16x32_bf16 v[92:95], v[164:167], v[12:15], v[92:95]
	v_mfma_f32_16x16x32_bf16 v[96:99], v[164:167], v[28:31], v[96:99]
	ds_read_b128 v[164:167], v1 offset:47488
	ds_read_b128 v[196:199], v1 offset:47552
	s_waitcnt lgkmcnt(0)
	v_mfma_f32_16x16x32_bf16 v[100:103], v[164:167], v[12:15], v[100:103]
	v_mfma_f32_16x16x32_bf16 v[142:145], v[164:167], v[28:31], v[142:145]
	v_mfma_f32_16x16x32_bf16 v[164:167], v[168:171], v[16:19], v[68:71]
	v_mfma_f32_16x16x32_bf16 v[168:171], v[168:171], v[32:35], v[60:63]
	v_mfma_f32_16x16x32_bf16 v[200:203], v[172:175], v[16:19], v[64:67]
	s_nop 5
	v_fma_f32 v2, -v164, s50, v114
	v_fma_f32 v3, -v165, s50, v115
	v_pk_fma_f32 v[60:61], v[168:169], s[50:51], v[116:117] op_sel_hi:[1,0,1] neg_lo:[1,0,0] neg_hi:[1,0,0]
	v_min_f32_e32 v1, 0x42700000, v2
	v_min_f32_e32 v3, 0x42700000, v3
	v_min_f32_e32 v60, 0x42700000, v60
	v_min_f32_e32 v61, 0x42700000, v61
	v_exp_f32_e32 v2, v1
	v_exp_f32_e32 v3, v3
	v_exp_f32_e32 v64, v60
	v_exp_f32_e32 v65, v61
	v_mfma_f32_16x16x32_bf16 v[68:71], v[192:195], v[16:19], v[92:95]
	v_add_f32_e64 v2, v2, 1.0
	v_add_f32_e64 v3, v3, 1.0
	v_add_u32_e32 v1, s16, v126
	s_lshl_b32 s16, s34, 14
	v_pk_add_f32 v[92:93], v[64:65], 1.0 op_sel_hi:[1,0]
	v_mfma_f32_16x16x32_bf16 v[172:175], v[172:175], v[32:35], v[84:87]
	v_mul_f32_e64 v64, v92, v2
	v_mul_f32_e64 v65, v93, v3
	v_pk_fma_f32 v[68:69], v[68:69], s[50:51], v[114:115] op_sel_hi:[1,0,1] neg_lo:[1,0,0] neg_hi:[1,0,0]
	v_rcp_f32_e32 v94, v64
	v_rcp_f32_e32 v95, v65
	v_mfma_f32_16x16x32_bf16 v[84:87], v[192:195], v[32:35], v[96:99]
	v_min_f32_e32 v68, 0x42700000, v68
	v_min_f32_e32 v69, 0x42700000, v69
	v_pk_mul_f32 v[92:93], v[92:93], v[94:95]
	v_mfma_f32_16x16x32_bf16 v[60:63], v[196:199], v[16:19], v[100:103]
	v_mul_f32_e64 v92, v118, v92
	v_mul_f32_e64 v93, v119, v93
	v_pk_fma_f32 v[98:99], v[166:167], s[50:51], v[114:115] op_sel_hi:[1,0,1] neg_lo:[1,0,0] neg_hi:[1,0,0]
	v_exp_f32_e32 v92, v92
	v_pk_fma_f32 v[100:101], v[170:171], s[50:51], v[116:117] op_sel_hi:[1,0,1] neg_lo:[1,0,0] neg_hi:[1,0,0]
	v_exp_f32_e32 v93, v93
	v_min_f32_e32 v98, 0x42700000, v98
	v_min_f32_e32 v99, 0x42700000, v99
	v_min_f32_e32 v100, 0x42700000, v100
	v_min_f32_e32 v101, 0x42700000, v101
	v_exp_f32_e32 v98, v98
	v_exp_f32_e32 v99, v99
	v_exp_f32_e32 v100, v100
	v_exp_f32_e32 v101, v101
	v_pk_mul_f32 v[2:3], v[2:3], v[94:95]
	v_pk_fma_f32 v[94:95], v[92:93], v[92:93], 1.0 op_sel_hi:[1,1,0] neg_lo:[1,0,0] neg_hi:[1,0,0]
	v_pk_add_f32 v[98:99], v[98:99], 1.0 op_sel_hi:[1,0]
	v_max_f32_e32 v102, 0, v94
	v_max_f32_e32 v103, 0, v95
	v_pk_add_f32 v[94:95], v[100:101], 1.0 op_sel_hi:[1,0]
	v_mfma_f32_16x16x32_bf16 v[64:67], v[196:199], v[32:35], v[142:145]
	v_mul_f32_e64 v100, v94, v98
	v_mul_f32_e64 v101, v95, v99
	ds_read_u16 v96, v1 offset:34304
	ds_read_u16 v97, v1 offset:34576
	ds_read_u16 v141, v1 offset:34848
	ds_read_u16 v142, v1 offset:35120
	ds_read_u16 v164, v1 offset:38656
	ds_read_u16 v165, v1 offset:38928
	ds_read_u16 v168, v1 offset:39200
	ds_read_u16 v169, v1 offset:39472
	v_rcp_f32_e32 v100, v100
	v_rcp_f32_e32 v101, v101
	s_waitcnt lgkmcnt(0)
; #define LAS __attribute__((address_space(3)))
; __device__ __forceinline__ float bf_1(bf16_t h) { return __uint_as_float(((unsigned)h) << 16); }
; template <int DIR>
; __device__ __forceinline__ void rnn_item(LAS unsigned char* lds, const bf16_t* proj, bf16_t* hout, int hpitch, int layer, int s, int n) {
;     ...
;                 for (int rp = 0; rp < 2; ++rp) {
;                     const LAS unsigned char* xp = At + buf * 17408 + (mt * 16 + kg * 4 + 2 * rp) * 272 + (w * 16 + l16) * 2;
;                     const f32x2 xc = {bf_1(*(const LAS bf16_t*)xp), bf_1(*(const LAS bf16_t*)(xp + 272))};
;                     const f32x2 xa = {aA[mt][2 * rp], aA[mt][2 * rp + 1]}, xx = {aX[mt][2 * rp], aX[mt][2 * rp + 1]};
;                     f32x2 ta = xa * (-LOG2E) + nba, tx = xx * (-LOG2E) + nbx;
;                     ta.x = fminf(ta.x, 60.f); ta.y = fminf(ta.y, 60.f); tx.x = fminf(tx.x, 60.f); tx.y = fminf(tx.y, 60.f);
;                     f32x2 ea, ex; ea.x = __builtin_amdgcn_exp2f(ta.x); ea.y = __builtin_amdgcn_exp2f(ta.y); ex.x = __builtin_amdgcn_exp2f(tx.x); ex.y = __builtin_amdgcn_exp2f(tx.y);
;                     const f32x2 da = ea + 1.0f, dx = ex + 1.0f, dd = da * dx;
;                     f32x2 inv; inv.x = __builtin_amdgcn_rcpf(dd.x); inv.y = __builtin_amdgcn_rcpf(dd.y);
;                     const f32x2 rr = dx * inv, ii = da * inv, tt = rr * clam2;
;                     f32x2 av; av.x = __builtin_amdgcn_exp2f(tt.x); av.y = __builtin_amdgcn_exp2f(tt.y);
;                     f32x2 om = 1.0f - av * av; om.x = fmaxf(om.x, 0.f); om.y = fmaxf(om.y, 0.f);
;                     f32x2 sq; sq.x = __builtin_amdgcn_sqrtf(om.x); sq.y = __builtin_amdgcn_sqrtf(om.y);
;                     const f32x2 bv = sq * (ii * xc);
;                     aA[mt][2 * rp] = av.x; aA[mt][2 * rp + 1] = av.y; aX[mt][2 * rp] = bv.x; aX[mt][2 * rp + 1] = bv.y;
	v_lshlrev_b32_e32 v96, 16, v96
	v_lshlrev_b32_e32 v97, 16, v97
	v_pk_mul_f32 v[96:97], v[2:3], v[96:97]
	v_pk_mul_f32 v[2:3], v[94:95], v[100:101]
	v_sqrt_f32_e32 v102, v102
	v_pk_mul_f32 v[2:3], v[118:119], v[2:3]
	v_sqrt_f32_e32 v103, v103
	v_exp_f32_e32 v2, v2
	v_exp_f32_e32 v3, v3
	v_pk_mul_f32 v[98:99], v[98:99], v[100:101]
	v_pk_mul_f32 v[94:95], v[96:97], v[102:103]
	v_lshlrev_b32_e32 v96, 16, v141
	v_pk_fma_f32 v[102:103], v[2:3], v[2:3], 1.0 op_sel_hi:[1,1,0] neg_lo:[1,0,0] neg_hi:[1,0,0]
	v_lshlrev_b32_e32 v97, 16, v142
	v_max_f32_e32 v141, 0, v102
	v_max_f32_e32 v145, 0, v103
	v_pk_fma_f32 v[102:103], v[200:201], s[50:51], v[114:115] op_sel_hi:[1,0,1] neg_lo:[1,0,0] neg_hi:[1,0,0]
	v_pk_fma_f32 v[142:143], v[172:173], s[50:51], v[116:117] op_sel_hi:[1,0,1] neg_lo:[1,0,0] neg_hi:[1,0,0]
	v_min_f32_e32 v102, 0x42700000, v102
	v_min_f32_e32 v103, 0x42700000, v103
	v_min_f32_e32 v142, 0x42700000, v142
	v_min_f32_e32 v143, 0x42700000, v143
	v_exp_f32_e32 v102, v102
	v_exp_f32_e32 v103, v103
	v_exp_f32_e32 v142, v142
	v_exp_f32_e32 v143, v143
	v_sqrt_f32_e32 v144, v141
	v_pk_add_f32 v[146:147], v[102:103], 1.0 op_sel_hi:[1,0]
	v_sqrt_f32_e32 v145, v145
	v_pk_add_f32 v[102:103], v[142:143], 1.0 op_sel_hi:[1,0]
	v_pk_mul_f32 v[96:97], v[98:99], v[96:97]
	v_pk_mul_f32 v[142:143], v[102:103], v[146:147]
	v_pk_mul_f32 v[96:97], v[96:97], v[144:145]
	v_rcp_f32_e32 v142, v142
	v_rcp_f32_e32 v143, v143
	v_pk_fma_f32 v[144:145], v[202:203], s[50:51], v[114:115] op_sel_hi:[1,0,1] neg_lo:[1,0,0] neg_hi:[1,0,0]
	v_pk_fma_f32 v[84:85], v[84:85], s[50:51], v[116:117] op_sel_hi:[1,0,1] neg_lo:[1,0,0] neg_hi:[1,0,0]
	v_min_f32_e32 v141, 0x42700000, v144
	v_pk_mul_f32 v[98:99], v[102:103], v[142:143]
	v_pk_mul_f32 v[100:101], v[146:147], v[142:143]
	v_pk_mul_f32 v[98:99], v[118:119], v[98:99]
	v_pk_fma_f32 v[146:147], v[174:175], s[50:51], v[116:117] op_sel_hi:[1,0,1] neg_lo:[1,0,0] neg_hi:[1,0,0]
	v_exp_f32_e32 v102, v98
	v_exp_f32_e32 v103, v99
	v_min_f32_e32 v145, 0x42700000, v145
	v_min_f32_e32 v146, 0x42700000, v146
	v_min_f32_e32 v147, 0x42700000, v147
	v_exp_f32_e32 v144, v141
	v_exp_f32_e32 v145, v145
	v_exp_f32_e32 v146, v146
	v_exp_f32_e32 v147, v147
	v_pk_fma_f32 v[142:143], v[102:103], v[102:103], 1.0 op_sel_hi:[1,1,0] neg_lo:[1,0,0] neg_hi:[1,0,0]
	v_min_f32_e32 v84, 0x42700000, v84
	v_min_f32_e32 v85, 0x42700000, v85
	v_lshlrev_b32_e32 v99, 16, v165
	v_max_f32_e32 v141, 0, v142
	v_max_f32_e32 v165, 0, v143
	v_pk_add_f32 v[142:143], v[144:145], 1.0 op_sel_hi:[1,0]
	v_pk_add_f32 v[144:145], v[146:147], 1.0 op_sel_hi:[1,0]
	v_exp_f32_e32 v68, v68
	v_exp_f32_e32 v69, v69
	v_exp_f32_e32 v84, v84
	v_exp_f32_e32 v85, v85
	v_pk_mul_f32 v[146:147], v[144:145], v[142:143]
	v_pk_add_f32 v[166:167], v[68:69], 1.0 op_sel_hi:[1,0]
	v_rcp_f32_e32 v146, v146
	v_rcp_f32_e32 v147, v147
	v_pk_add_f32 v[84:85], v[84:85], 1.0 op_sel_hi:[1,0]
	v_lshlrev_b32_e32 v98, 16, v164
	v_pk_mul_f32 v[68:69], v[84:85], v[166:167]
	v_pk_mul_f32 v[100:101], v[100:101], v[98:99]
	v_pk_mul_f32 v[98:99], v[144:145], v[146:147]
	v_lshlrev_b32_e32 v144, 16, v168
	v_lshlrev_b32_e32 v145, 16, v169
	v_rcp_f32_e32 v168, v68
	v_rcp_f32_e32 v169, v69
	v_pk_mul_f32 v[98:99], v[118:119], v[98:99]
	v_sqrt_f32_e32 v164, v141
	v_sqrt_f32_e32 v165, v165
	v_exp_f32_e32 v98, v98
	v_exp_f32_e32 v99, v99
	v_pk_mul_f32 v[84:85], v[84:85], v[168:169]
	v_pk_fma_f32 v[70:71], v[70:71], s[50:51], v[114:115] op_sel_hi:[1,0,1] neg_lo:[1,0,0] neg_hi:[1,0,0]
	v_pk_fma_f32 v[86:87], v[86:87], s[50:51], v[116:117] op_sel_hi:[1,0,1] neg_lo:[1,0,0] neg_hi:[1,0,0]
	v_pk_mul_f32 v[84:85], v[118:119], v[84:85]
	v_min_f32_e32 v70, 0x42700000, v70
	v_min_f32_e32 v71, 0x42700000, v71
	v_min_f32_e32 v86, 0x42700000, v86
	v_min_f32_e32 v87, 0x42700000, v87
	v_pk_mul_f32 v[68:69], v[142:143], v[146:147]
	v_exp_f32_e32 v142, v84
	v_exp_f32_e32 v143, v85
	v_exp_f32_e32 v70, v70
	v_exp_f32_e32 v71, v71
	v_exp_f32_e32 v86, v86
	v_exp_f32_e32 v87, v87
	v_pk_mul_f32 v[100:101], v[100:101], v[164:165]
	v_pk_fma_f32 v[164:165], v[98:99], v[98:99], 1.0 op_sel_hi:[1,1,0] neg_lo:[1,0,0] neg_hi:[1,0,0]
	v_pk_mul_f32 v[68:69], v[68:69], v[144:145]
	v_max_f32_e32 v141, 0, v164
	v_max_f32_e32 v165, 0, v165
	v_sqrt_f32_e32 v164, v141
	v_sqrt_f32_e32 v165, v165
	v_pk_fma_f32 v[144:145], v[142:143], v[142:143], 1.0 op_sel_hi:[1,1,0] neg_lo:[1,0,0] neg_hi:[1,0,0]
	v_pk_add_f32 v[146:147], v[70:71], 1.0 op_sel_hi:[1,0]
	v_pk_add_f32 v[70:71], v[86:87], 1.0 op_sel_hi:[1,0]
	v_pk_fma_f32 v[60:61], v[60:61], s[50:51], v[114:115] op_sel_hi:[1,0,1] neg_lo:[1,0,0] neg_hi:[1,0,0]
	v_pk_fma_f32 v[64:65], v[64:65], s[50:51], v[116:117] op_sel_hi:[1,0,1] neg_lo:[1,0,0] neg_hi:[1,0,0]
	v_max_f32_e32 v144, 0, v144
	v_max_f32_e32 v145, 0, v145
	v_pk_mul_f32 v[86:87], v[70:71], v[146:147]
	v_min_f32_e32 v60, 0x42700000, v60
	v_min_f32_e32 v61, 0x42700000, v61
	v_min_f32_e32 v64, 0x42700000, v64
	v_min_f32_e32 v65, 0x42700000, v65
	v_sqrt_f32_e32 v144, v144
	v_sqrt_f32_e32 v145, v145
	v_rcp_f32_e32 v86, v86
	v_rcp_f32_e32 v87, v87
	v_exp_f32_e32 v60, v60
	v_exp_f32_e32 v61, v61
	v_exp_f32_e32 v64, v64
	v_exp_f32_e32 v65, v65
	ds_read_u16 v84, v1 offset:43008
	ds_read_u16 v85, v1 offset:43280
	ds_read_u16 v141, v1 offset:43552
	ds_read_u16 v170, v1 offset:43824
	ds_read_u16 v171, v1 offset:47360
	ds_read_u16 v172, v1 offset:47632
	ds_read_u16 v173, v1 offset:47904
	ds_read_u16 v1, v1 offset:48176
	v_pk_mul_f32 v[68:69], v[68:69], v[164:165]
	s_waitcnt lgkmcnt(0)
; template <int DIR>
; __device__ __forceinline__ void rnn_item(LAS unsigned char* lds, const bf16_t* proj, bf16_t* hout, int hpitch, int layer, int s, int n) {
;     ...
; #pragma unroll
;         for (int mt = 0; mt < 4; ++mt) {
;             float pp = 1.f, hh = 0.f;
; #pragma unroll
;             for (int q = 0; q < 4; ++q) { const int r = DIR == 0 ? q : 3 - q; hh = aA[mt][r] * hh + aX[mt][r]; pp *= aA[mt][r]; aA[mt][r] = pp; aX[mt][r] = hh; }
;         }
;         float start[4]; float carry = hcarry;
; #pragma unroll
;         for (int hq = 0; hq < 2; ++hq) {
;             float Ar[8], Br[8];
; #pragma unroll
;             for (int q8 = 0; q8 < 8; ++q8) { const int q = hq * 8 + q8; const int rho = DIR == 0 ? q : 15 - q; const int mt = rho >> 2, kgp = rho & 3; constexpr int re = DIR == 0 ? 3 : 0;
;                 Ar[q8] = __shfl(aA[mt][re], l16 + 16 * kgp); Br[q8] = __shfl(aX[mt][re], l16 + 16 * kgp); }
; #pragma unroll
;             for (int q8 = 0; q8 < 8; ++q8) { const int q = hq * 8 + q8; const int rho = DIR == 0 ? q : 15 - q; const int mt = rho >> 2, kgp = rho & 3;
;                 if (kg == kgp) start[mt] = carry;
;                 carry = Ar[q8] * carry + Br[q8]; }
	v_lshlrev_b32_e32 v84, 16, v84
	v_lshlrev_b32_e32 v85, 16, v85
	v_pk_mul_f32 v[164:165], v[166:167], v[168:169]
	v_pk_fma_f32 v[62:63], v[62:63], s[50:51], v[114:115] op_sel_hi:[1,0,1] neg_lo:[1,0,0] neg_hi:[1,0,0]
	v_pk_mul_f32 v[84:85], v[164:165], v[84:85]
	v_pk_fma_f32 v[66:67], v[66:67], s[50:51], v[116:117] op_sel_hi:[1,0,1] neg_lo:[1,0,0] neg_hi:[1,0,0]
	v_pk_mul_f32 v[84:85], v[84:85], v[144:145]
	v_pk_mul_f32 v[70:71], v[70:71], v[86:87]
	v_lshlrev_b32_e32 v144, 16, v141
	v_lshlrev_b32_e32 v145, 16, v170
	v_pk_mul_f32 v[86:87], v[146:147], v[86:87]
	v_pk_add_f32 v[60:61], v[60:61], 1.0 op_sel_hi:[1,0]
	v_pk_add_f32 v[64:65], v[64:65], 1.0 op_sel_hi:[1,0]
	v_min_f32_e32 v62, 0x42700000, v62
	v_min_f32_e32 v63, 0x42700000, v63
	v_min_f32_e32 v66, 0x42700000, v66
	v_min_f32_e32 v67, 0x42700000, v67
	v_pk_mul_f32 v[86:87], v[86:87], v[144:145]
	v_pk_mul_f32 v[144:145], v[64:65], v[60:61]
	v_exp_f32_e32 v62, v62
	v_exp_f32_e32 v63, v63
	v_exp_f32_e32 v66, v66
	v_exp_f32_e32 v67, v67
	v_rcp_f32_e32 v144, v144
	v_rcp_f32_e32 v145, v145
	v_pk_mul_f32 v[70:71], v[118:119], v[70:71]
	v_pk_add_f32 v[62:63], v[62:63], 1.0 op_sel_hi:[1,0]
	v_pk_add_f32 v[66:67], v[66:67], 1.0 op_sel_hi:[1,0]
	v_exp_f32_e32 v70, v70
	v_exp_f32_e32 v71, v71
	v_pk_mul_f32 v[64:65], v[64:65], v[144:145]
	v_pk_mul_f32 v[164:165], v[66:67], v[62:63]
	v_pk_mul_f32 v[64:65], v[118:119], v[64:65]
	v_rcp_f32_e32 v164, v164
	v_rcp_f32_e32 v165, v165
	v_exp_f32_e32 v64, v64
	v_exp_f32_e32 v65, v65
	v_pk_fma_f32 v[146:147], v[70:71], v[70:71], 1.0 op_sel_hi:[1,1,0] neg_lo:[1,0,0] neg_hi:[1,0,0]
	v_pk_mul_f32 v[66:67], v[66:67], v[164:165]
	v_max_f32_e32 v141, 0, v146
	v_max_f32_e32 v147, 0, v147
	v_sqrt_f32_e32 v146, v141
	v_sqrt_f32_e32 v147, v147
	v_pk_mul_f32 v[60:61], v[60:61], v[144:145]
	v_pk_fma_f32 v[144:145], v[64:65], v[64:65], 1.0 op_sel_hi:[1,1,0] neg_lo:[1,0,0] neg_hi:[1,0,0]
	v_pk_mul_f32 v[66:67], v[118:119], v[66:67]
	v_max_f32_e32 v141, 0, v144
	v_max_f32_e32 v145, 0, v145
	v_exp_f32_e32 v66, v66
	v_exp_f32_e32 v67, v67
	v_sqrt_f32_e32 v144, v141
	v_sqrt_f32_e32 v145, v145
	v_pk_mul_f32 v[86:87], v[86:87], v[146:147]
	v_lshlrev_b32_e32 v146, 16, v171
	v_lshlrev_b32_e32 v147, 16, v172
	v_pk_mul_f32 v[60:61], v[60:61], v[146:147]
	v_pk_fma_f32 v[146:147], v[66:67], v[66:67], 1.0 op_sel_hi:[1,1,0] neg_lo:[1,0,0] neg_hi:[1,0,0]
	v_pk_mul_f32 v[144:145], v[60:61], v[144:145]
	v_max_f32_e32 v61, 0, v146
	v_max_f32_e32 v141, 0, v147
	v_sqrt_f32_e32 v146, v61
	v_sqrt_f32_e32 v147, v141
	v_lshlrev_b32_e32 v60, 16, v173
	v_lshlrev_b32_e32 v61, 16, v1
	v_pk_mul_f32 v[62:63], v[62:63], v[164:165]
	v_fma_f32 v69, 0, v99, v69
	v_fma_f32 v87, 0, v71, v87
	v_pk_mul_f32 v[60:61], v[62:63], v[60:61]
	v_fma_f32 v1, 0, v3, v97
	v_fmac_f32_e32 v68, v98, v69
	v_mul_f32_e32 v97, v99, v98
	v_fmac_f32_e32 v86, v70, v87
	v_mul_f32_e32 v70, v71, v70
	v_pk_mul_f32 v[146:147], v[60:61], v[146:147]
	v_fma_f32 v98, v103, v68, v101
	v_mul_f32_e32 v101, v103, v97
	v_fma_f32 v85, v143, v86, v85
	v_mul_f32_e32 v103, v143, v70
	v_fmac_f32_e32 v84, v142, v85
	v_mul_f32_e32 v141, v142, v103
	v_fma_f32 v142, 0, v67, v147
	v_fmac_f32_e32 v146, v66, v142
	v_mul_f32_e32 v66, v67, v66
	v_fma_f32 v143, v65, v146, v145
	v_mul_f32_e32 v65, v65, v66
	v_fmac_f32_e32 v144, v64, v143
	v_mul_f32_e32 v64, v64, v65
	ds_bpermute_b32 v60, v128, v64
	ds_bpermute_b32 v61, v128, v144
	ds_bpermute_b32 v62, v129, v64
	ds_bpermute_b32 v63, v129, v144
	ds_bpermute_b32 v145, v130, v64
	ds_bpermute_b32 v147, v130, v144
	ds_bpermute_b32 v164, v123, v64
	ds_bpermute_b32 v165, v123, v144
	ds_bpermute_b32 v166, v128, v141
	ds_bpermute_b32 v167, v128, v84
	ds_bpermute_b32 v168, v129, v141
	ds_bpermute_b32 v169, v129, v84
	s_waitcnt lgkmcnt(0)
; #define LAS __attribute__((address_space(3)))
; __device__ __forceinline__ unsigned cvt_pk_bf16(float lo, float hi) { unsigned r; asm volatile("v_cvt_pk_bf16_f32 %0, %1, %2" : "=v"(r) : "v"(lo), "v"(hi)); return r; }
; #define RNN_BAR() do { asm volatile("s_waitcnt lgkmcnt(0)" ::: "memory"); __builtin_amdgcn_s_barrier(); asm volatile("" ::: "memory"); } while (0)
; template <int DIR>
; __device__ __forceinline__ void rnn_item(LAS unsigned char* lds, const bf16_t* proj, bf16_t* hout, int hpitch, int layer, int s, int n) {
;     ...
;         float start[4]; float carry = hcarry;
; #pragma unroll
;         for (int hq = 0; hq < 2; ++hq) {
;             float Ar[8], Br[8];
; #pragma unroll
;             for (int q8 = 0; q8 < 8; ++q8) { const int q = hq * 8 + q8; const int rho = DIR == 0 ? q : 15 - q; const int mt = rho >> 2, kgp = rho & 3; constexpr int re = DIR == 0 ? 3 : 0;
;                 Ar[q8] = __shfl(aA[mt][re], l16 + 16 * kgp); Br[q8] = __shfl(aX[mt][re], l16 + 16 * kgp); }
; #pragma unroll
;             for (int q8 = 0; q8 < 8; ++q8) { const int q = hq * 8 + q8; const int rho = DIR == 0 ? q : 15 - q; const int mt = rho >> 2, kgp = rho & 3;
;                 if (kg == kgp) start[mt] = carry;
;                 carry = Ar[q8] * carry + Br[q8]; }
;         }
;         hcarry = carry;
;         if (it > 0) {
; #pragma unroll
;             for (int i = 0; i < 2; ++i) { const int c = tid + 512 * i; const u32x4 v = *(const LAS u32x4*)(OUTB + (buf ^ 1) * 16384 + c * 16);
;                 *(u32x4*)(hout + (seqbase + (size_t)(sub - stp) * 64 + (c >> 4)) * hpitch + n * 128 + (c & 15) * 8) = v; }
;         }
;         {   LAS unsigned short* ob = (LAS unsigned short*)(OUTB + buf * 16384 + (kg * 4) * 256 + (w * 16 + l16) * 2);
; #pragma unroll
;             for (int mt = 0; mt < 4; ++mt)
; #pragma unroll
;                 for (int rp = 0; rp < 2; ++rp) {
;                     const float h0 = aX[mt][2 * rp] + aA[mt][2 * rp] * start[mt], h1 = aX[mt][2 * rp + 1] + aA[mt][2 * rp + 1] * start[mt];
;                     const unsigned pk = cvt_pk_bf16(h0, h1);
;                     ob[(mt * 16 + 2 * rp) * 128] = (unsigned short)(pk & 0xffffu); ob[(mt * 16 + 2 * rp + 1) * 128] = (unsigned short)(pk >> 16);
;                 }
;         }
;         RNN_BAR();
	v_fmac_f32_e32 v61, v135, v60
	ds_bpermute_b32 v170, v130, v141
	ds_bpermute_b32 v171, v130, v84
	v_fmac_f32_e32 v63, v61, v62
	v_cndmask_b32_e64 v60, v131, v61, s[8:9]
	v_fmac_f32_e32 v147, v63, v145
	v_cndmask_b32_e64 v60, v60, v63, s[10:11]
	v_fmac_f32_e32 v165, v147, v164
	v_cndmask_b32_e64 v131, v60, v147, s[12:13]
	v_cndmask_b32_e64 v60, v132, v165, s[6:7]
	v_fmac_f32_e32 v167, v165, v166
	v_cndmask_b32_e64 v60, v60, v167, s[8:9]
	v_fmac_f32_e32 v169, v167, v168
	v_fmac_f32_e32 v100, v102, v98
	v_mul_f32_e32 v102, v102, v101
	ds_bpermute_b32 v172, v123, v141
	ds_bpermute_b32 v173, v123, v84
	v_cndmask_b32_e64 v60, v60, v169, s[10:11]
	s_waitcnt lgkmcnt(0)
	v_fmac_f32_e32 v171, v169, v170
	v_cndmask_b32_e64 v132, v60, v171, s[12:13]
	ds_bpermute_b32 v60, v128, v102
	ds_bpermute_b32 v61, v128, v100
	ds_bpermute_b32 v62, v129, v102
	ds_bpermute_b32 v63, v129, v100
	ds_bpermute_b32 v145, v130, v102
	ds_bpermute_b32 v147, v130, v100
	v_fmac_f32_e32 v173, v171, v172
	v_cndmask_b32_e64 v133, v133, v173, s[6:7]
	s_waitcnt lgkmcnt(0)
	v_fmac_f32_e32 v61, v173, v60
	s_xor_b32 s17, s16, 0x4000
	v_cndmask_b32_e64 v60, v133, v61, s[8:9]
	v_fmac_f32_e32 v63, v61, v62
	s_add_i32 s17, s17, 0
	v_cndmask_b32_e64 v60, v60, v63, s[10:11]
	v_fmac_f32_e32 v147, v63, v145
	s_add_i32 s17, s17, 0x11800
	v_fmac_f32_e32 v96, v2, v1
	v_mul_f32_e32 v2, v3, v2
	v_cndmask_b32_e64 v133, v60, v147, s[12:13]
	v_add_u32_e32 v60, s17, v113
	v_fma_f32 v95, v93, v96, v95
	v_mul_f32_e32 v93, v93, v2
	ds_read_b128 v[60:63], v60
	v_fmac_f32_e32 v94, v92, v95
	v_mul_f32_e32 v92, v92, v93
	ds_bpermute_b32 v164, v123, v102
	ds_bpermute_b32 v165, v123, v100
	ds_bpermute_b32 v166, v128, v92
	ds_bpermute_b32 v167, v128, v94
	ds_bpermute_b32 v168, v129, v92
	ds_bpermute_b32 v169, v129, v94
	ds_bpermute_b32 v170, v130, v92
	ds_bpermute_b32 v171, v130, v94
	s_waitcnt lgkmcnt(0)
	global_store_dwordx4 v[90:91], v[60:63], off
	v_fmac_f32_e32 v165, v147, v164
	v_cndmask_b32_e64 v134, v134, v165, s[6:7]
	v_add_u32_e32 v60, s17, v121
	ds_read_b128 v[60:63], v60
	v_fmac_f32_e32 v167, v165, v166
	v_cndmask_b32_e64 v134, v134, v167, s[8:9]
	v_fmac_f32_e32 v169, v167, v168
	v_cndmask_b32_e64 v134, v134, v169, s[10:11]
	v_fmac_f32_e32 v171, v169, v170
	v_cndmask_b32_e64 v134, v134, v171, s[12:13]
	ds_bpermute_b32 v135, v123, v94
	s_waitcnt lgkmcnt(0)
	global_store_dwordx4 v[88:89], v[60:63], off
	v_fmac_f32_e32 v94, v92, v134
	v_fmac_f32_e32 v95, v93, v134
	v_add_u32_e32 v60, s16, v124
	v_cvt_pk_bf16_f32 v61, v94, v95
	v_fmac_f32_e32 v1, v3, v134
	ds_write_b16 v60, v61
	ds_write_b16_d16_hi v60, v61 offset:256
	v_fmac_f32_e32 v96, v2, v134
	v_cvt_pk_bf16_f32 v1, v96, v1
	ds_write_b16 v60, v1 offset:512
	ds_write_b16_d16_hi v60, v1 offset:768
	v_fmac_f32_e32 v100, v102, v133
	v_fmac_f32_e32 v98, v101, v133
	v_cvt_pk_bf16_f32 v1, v100, v98
	ds_write_b16 v60, v1 offset:4096
	ds_write_b16_d16_hi v60, v1 offset:4352
	v_fmac_f32_e32 v68, v97, v133
	v_fmac_f32_e32 v69, v99, v133
	v_cvt_pk_bf16_f32 v1, v68, v69
	ds_write_b16 v60, v1 offset:4608
	ds_write_b16_d16_hi v60, v1 offset:4864
	v_fmac_f32_e32 v84, v141, v132
	v_fmac_f32_e32 v85, v103, v132
	v_cvt_pk_bf16_f32 v1, v84, v85
	ds_write_b16 v60, v1 offset:8192
	ds_write_b16_d16_hi v60, v1 offset:8448
	v_fmac_f32_e32 v86, v70, v132
	v_fmac_f32_e32 v87, v71, v132
	v_cvt_pk_bf16_f32 v1, v86, v87
	ds_bpermute_b32 v172, v123, v92
	ds_write_b16 v60, v1 offset:8704
	ds_write_b16_d16_hi v60, v1 offset:8960
	v_fmac_f32_e32 v144, v64, v131
	v_fmac_f32_e32 v143, v65, v131
	v_cvt_pk_bf16_f32 v1, v144, v143
	ds_write_b16 v60, v1 offset:12288
	ds_write_b16_d16_hi v60, v1 offset:12544
	v_fmac_f32_e32 v146, v66, v131
	v_fmac_f32_e32 v142, v67, v131
	v_cvt_pk_bf16_f32 v1, v146, v142
	ds_write_b16 v60, v1 offset:12800
	ds_write_b16_d16_hi v60, v1 offset:13056
	s_waitcnt lgkmcnt(0)
	s_barrier
	s_mov_b32 s16, 0xfffe0000
	s_mov_b32 s17, -1
	s_waitcnt lgkmcnt(0)
	v_fmac_f32_e32 v135, v171, v172
	v_lshl_add_u64 v[88:89], v[88:89], 0, s[16:17]
	v_lshl_add_u64 v[90:91], v[90:91], 0, s[16:17]
	s_cmp_lg_u32 s19, 0xfc870000
	s_cbranch_scc0 .LBB0_554

.LBB0_609:
	s_or_b64 exec, exec, s[16:17]
	s_xor_b32 s16, s34, 1
	s_mul_i32 s17, s16, 0x4300
	v_add_u32_e32 v1, s17, v107
	ds_read_b128 v[64:67], v1
	ds_read_b128 v[68:71], v1 offset:256
	ds_read_b128 v[84:87], v1 offset:512
	ds_read_b128 v[92:95], v1 offset:768
	ds_read_b128 v[60:63], v1 offset:1024
	ds_read_b128 v[96:99], v120
	ds_read_b128 v[100:103], v120 offset:16
	ds_read_b128 v[142:145], v120 offset:512
	ds_read_b128 v[164:167], v120 offset:528
	ds_read_b128 v[168:171], v120 offset:1024
	ds_read_b128 v[204:207], v120 offset:1040
	ds_read_b128 v[172:175], v120 offset:1536
	ds_read_b128 v[192:195], v120 offset:1552
	ds_read_b128 v[196:199], v120 offset:2048
	ds_read_b128 v[200:203], v120 offset:2064
	s_mulk_i32 s16, 0x4400
	v_add_u32_e32 v2, s16, v112
	s_mul_i32 s16, s34, 0x4400
	v_cndmask_b32_e64 v132, v132, v136, s[6:7]
	s_add_i32 s31, s31, 1
	s_add_i32 s19, s19, 0x38000
	s_add_i32 s30, s30, 64
	s_waitcnt lgkmcnt(0)
	v_lshlrev_b32_e32 v208, 16, v64
	v_and_b32_e32 v209, 0xffff0000, v64
	v_lshlrev_b32_e32 v210, 16, v68
	v_and_b32_e32 v211, 0xffff0000, v68
	v_lshlrev_b32_e32 v212, 16, v84
	v_and_b32_e32 v213, 0xffff0000, v84
	v_lshlrev_b32_e32 v214, 16, v92
	v_and_b32_e32 v215, 0xffff0000, v92
	v_lshlrev_b32_e32 v216, 16, v60
	v_and_b32_e32 v217, 0xffff0000, v60
	v_fma_f32 v218, v96, v208, v196
	v_fmac_f32_e32 v218, v142, v210
	v_fmac_f32_e32 v218, v168, v212
	v_fmac_f32_e32 v218, v172, v214
	v_fma_f32 v226, v96, v210, v196
	v_fmac_f32_e32 v226, v142, v212
	v_fmac_f32_e32 v226, v168, v214
	v_fmac_f32_e32 v226, v172, v216
	v_fma_f32 v219, v97, v209, v197
	v_fmac_f32_e32 v219, v143, v211
	v_fmac_f32_e32 v219, v169, v213
	v_fmac_f32_e32 v219, v173, v215
	v_fma_f32 v227, v97, v211, v197
	v_fmac_f32_e32 v227, v143, v213
	v_fmac_f32_e32 v227, v169, v215
	v_fmac_f32_e32 v227, v173, v217
	v_lshlrev_b32_e32 v208, 16, v65
	v_and_b32_e32 v209, 0xffff0000, v65
	v_lshlrev_b32_e32 v210, 16, v69
	v_and_b32_e32 v211, 0xffff0000, v69
	v_lshlrev_b32_e32 v212, 16, v85
	v_and_b32_e32 v213, 0xffff0000, v85
	v_lshlrev_b32_e32 v214, 16, v93
	v_and_b32_e32 v215, 0xffff0000, v93
	v_lshlrev_b32_e32 v216, 16, v61
	v_and_b32_e32 v217, 0xffff0000, v61
	v_fma_f32 v220, v98, v208, v198
	v_fmac_f32_e32 v220, v144, v210
	v_fmac_f32_e32 v220, v170, v212
	v_fmac_f32_e32 v220, v174, v214
	v_fma_f32 v228, v98, v210, v198
	v_fmac_f32_e32 v228, v144, v212
	v_fmac_f32_e32 v228, v170, v214
	v_fmac_f32_e32 v228, v174, v216
	v_fma_f32 v221, v99, v209, v199
	v_fmac_f32_e32 v221, v145, v211
	v_fmac_f32_e32 v221, v171, v213
	v_fmac_f32_e32 v221, v175, v215
	v_fma_f32 v229, v99, v211, v199
	v_fmac_f32_e32 v229, v145, v213
	v_fmac_f32_e32 v229, v171, v215
	v_fmac_f32_e32 v229, v175, v217
	v_lshlrev_b32_e32 v208, 16, v66
	v_and_b32_e32 v209, 0xffff0000, v66
	v_lshlrev_b32_e32 v210, 16, v70
	v_and_b32_e32 v211, 0xffff0000, v70
	v_lshlrev_b32_e32 v212, 16, v86
	v_and_b32_e32 v213, 0xffff0000, v86
	v_lshlrev_b32_e32 v214, 16, v94
	v_and_b32_e32 v215, 0xffff0000, v94
	v_lshlrev_b32_e32 v216, 16, v62
	v_and_b32_e32 v217, 0xffff0000, v62
	v_fma_f32 v222, v100, v208, v200
	v_fmac_f32_e32 v222, v164, v210
	v_fmac_f32_e32 v222, v204, v212
	v_fmac_f32_e32 v222, v192, v214
	v_fma_f32 v230, v100, v210, v200
	v_fmac_f32_e32 v230, v164, v212
	v_fmac_f32_e32 v230, v204, v214
	v_fmac_f32_e32 v230, v192, v216
	v_fma_f32 v223, v101, v209, v201
	v_fmac_f32_e32 v223, v165, v211
	v_fmac_f32_e32 v223, v205, v213
	v_fmac_f32_e32 v223, v193, v215
	v_fma_f32 v231, v101, v211, v201
	v_fmac_f32_e32 v231, v165, v213
	v_fmac_f32_e32 v231, v205, v215
	v_fmac_f32_e32 v231, v193, v217
	v_lshlrev_b32_e32 v208, 16, v67
	v_and_b32_e32 v209, 0xffff0000, v67
	v_lshlrev_b32_e32 v210, 16, v71
	v_and_b32_e32 v211, 0xffff0000, v71
	v_lshlrev_b32_e32 v212, 16, v87
	v_and_b32_e32 v213, 0xffff0000, v87
	v_lshlrev_b32_e32 v214, 16, v95
	v_and_b32_e32 v215, 0xffff0000, v95
	v_lshlrev_b32_e32 v216, 16, v63
	v_and_b32_e32 v217, 0xffff0000, v63
	v_fma_f32 v224, v102, v208, v202
	v_fmac_f32_e32 v224, v166, v210
	v_fmac_f32_e32 v224, v206, v212
	v_fmac_f32_e32 v224, v194, v214
	v_fma_f32 v232, v102, v210, v202
	v_fmac_f32_e32 v232, v166, v212
	v_fmac_f32_e32 v232, v206, v214
	v_fmac_f32_e32 v232, v194, v216
	v_fma_f32 v225, v103, v209, v203
	v_fmac_f32_e32 v225, v167, v211
	v_fmac_f32_e32 v225, v207, v213
	v_fmac_f32_e32 v225, v195, v215
	v_fma_f32 v233, v103, v211, v203
	v_fmac_f32_e32 v233, v167, v213
	v_fmac_f32_e32 v233, v207, v215
	v_fmac_f32_e32 v233, v195, v217
	v_cvt_pk_bf16_f32 v234, v218, v219
	v_cvt_pk_bf16_f32 v235, v220, v221
	v_cvt_pk_bf16_f32 v236, v222, v223
	v_cvt_pk_bf16_f32 v237, v224, v225
	v_cvt_pk_bf16_f32 v238, v226, v227
	v_cvt_pk_bf16_f32 v239, v228, v229
	v_cvt_pk_bf16_f32 v240, v230, v231
	v_cvt_pk_bf16_f32 v241, v232, v233
	ds_write_b128 v2, v[234:237] offset:34304
	ds_write_b128 v2, v[238:241] offset:34576
	v_add_u32_e32 v1, s16, v127
	ds_read_b128 v[60:63], v1 offset:34304
	ds_read_b128 v[64:67], v1 offset:34368
	ds_read_b128 v[84:87], v1 offset:38656
	ds_read_b128 v[92:95], v1 offset:38720
	ds_read_b128 v[100:103], v1 offset:43008
	ds_read_b128 v[142:145], v1 offset:43072
	ds_read_b128 v[168:171], v1 offset:47360
	ds_read_b128 v[172:175], v1 offset:47424
	s_waitcnt lgkmcnt(0)
; #define LAS __attribute__((address_space(3)))
; __device__ __forceinline__ float bf_1(bf16_t h) { return __uint_as_float(((unsigned)h) << 16); }
; template <int DIR>
; __device__ __forceinline__ void rnn_item(LAS unsigned char* lds, const bf16_t* proj, bf16_t* hout, int hpitch, int layer, int s, int n) {
;     ...
; #pragma unroll
;         for (int ks = 0; ks < 4; ++ks)
; #pragma unroll
;             for (int mt = 0; mt < 4; ++mt) {
;                 const bf16x8 af = *(const LAS bf16x8*)(At + buf * 17408 + (mt * 16 + l16) * 272 + ks * 64 + kg * 16);
;                 aA[mt] = __builtin_amdgcn_mfma_f32_16x16x32_bf16(af, bfr[0][ks], aA[mt], 0, 0, 0);
;                 aX[mt] = __builtin_amdgcn_mfma_f32_16x16x32_bf16(af, bfr[1][ks], aX[mt], 0, 0, 0);
;             }
;         {   typedef float f32x2 __attribute__((ext_vector_type(2)));
; #pragma unroll
;             for (int mt = 0; mt < 4; ++mt)
; #pragma unroll
;                 for (int rp = 0; rp < 2; ++rp) {
;                     const LAS unsigned char* xp = At + buf * 17408 + (mt * 16 + kg * 4 + 2 * rp) * 272 + (w * 16 + l16) * 2;
;                     const f32x2 xc = {bf_1(*(const LAS bf16_t*)xp), bf_1(*(const LAS bf16_t*)(xp + 272))};
;                     const f32x2 xa = {aA[mt][2 * rp], aA[mt][2 * rp + 1]}, xx = {aX[mt][2 * rp], aX[mt][2 * rp + 1]};
;                     f32x2 ta = xa * (-LOG2E) + nba, tx = xx * (-LOG2E) + nbx;
;                     ta.x = fminf(ta.x, 60.f); ta.y = fminf(ta.y, 60.f); tx.x = fminf(tx.x, 60.f); tx.y = fminf(tx.y, 60.f);
;                     f32x2 ea, ex; ea.x = __builtin_amdgcn_exp2f(ta.x); ea.y = __builtin_amdgcn_exp2f(ta.y); ex.x = __builtin_amdgcn_exp2f(tx.x); ex.y = __builtin_amdgcn_exp2f(tx.y);
;                     const f32x2 da = ea + 1.0f, dx = ex + 1.0f, dd = da * dx;
;                     f32x2 inv; inv.x = __builtin_amdgcn_rcpf(dd.x); inv.y = __builtin_amdgcn_rcpf(dd.y);
;                     const f32x2 rr = dx * inv, ii = da * inv, tt = rr * clam2;
;                     f32x2 av; av.x = __builtin_amdgcn_exp2f(tt.x); av.y = __builtin_amdgcn_exp2f(tt.y);
;                     f32x2 om = 1.0f - av * av; om.x = fmaxf(om.x, 0.f); om.y = fmaxf(om.y, 0.f);
;                     f32x2 sq; sq.x = __builtin_amdgcn_sqrtf(om.x); sq.y = __builtin_amdgcn_sqrtf(om.y);
;                     const f32x2 bv = sq * (ii * xc);
	v_mfma_f32_16x16x32_bf16 v[68:71], v[60:63], v[4:7], 0
	v_mfma_f32_16x16x32_bf16 v[60:63], v[60:63], v[20:23], 0
	v_mfma_f32_16x16x32_bf16 v[96:99], v[84:87], v[4:7], 0
	v_mfma_f32_16x16x32_bf16 v[84:87], v[84:87], v[20:23], 0
	v_mfma_f32_16x16x32_bf16 v[164:167], v[100:103], v[4:7], 0
	v_mfma_f32_16x16x32_bf16 v[100:103], v[100:103], v[20:23], 0
	v_mfma_f32_16x16x32_bf16 v[192:195], v[168:171], v[4:7], 0
	v_mfma_f32_16x16x32_bf16 v[168:171], v[168:171], v[20:23], 0
	v_mfma_f32_16x16x32_bf16 v[68:71], v[64:67], v[8:11], v[68:71]
	v_mfma_f32_16x16x32_bf16 v[60:63], v[64:67], v[24:27], v[60:63]
	v_mfma_f32_16x16x32_bf16 v[64:67], v[92:95], v[8:11], v[96:99]
	v_mfma_f32_16x16x32_bf16 v[84:87], v[92:95], v[24:27], v[84:87]
	v_mfma_f32_16x16x32_bf16 v[92:95], v[142:145], v[8:11], v[164:167]
	v_mfma_f32_16x16x32_bf16 v[96:99], v[142:145], v[24:27], v[100:103]
	v_mfma_f32_16x16x32_bf16 v[142:145], v[172:175], v[24:27], v[168:171]
	s_nop 0
	ds_read_b128 v[164:167], v1 offset:34432
	s_nop 0
	ds_read_b128 v[168:171], v1 offset:34496
	v_mfma_f32_16x16x32_bf16 v[100:103], v[172:175], v[8:11], v[192:195]
	s_waitcnt lgkmcnt(0)
	v_mfma_f32_16x16x32_bf16 v[68:71], v[164:167], v[12:15], v[68:71]
	v_mfma_f32_16x16x32_bf16 v[60:63], v[164:167], v[28:31], v[60:63]
	ds_read_b128 v[164:167], v1 offset:38784
	ds_read_b128 v[172:175], v1 offset:38848
	s_waitcnt lgkmcnt(0)
	v_mfma_f32_16x16x32_bf16 v[64:67], v[164:167], v[12:15], v[64:67]
	v_mfma_f32_16x16x32_bf16 v[84:87], v[164:167], v[28:31], v[84:87]
	ds_read_b128 v[164:167], v1 offset:43136
	ds_read_b128 v[192:195], v1 offset:43200
	s_waitcnt lgkmcnt(0)
	v_mfma_f32_16x16x32_bf16 v[92:95], v[164:167], v[12:15], v[92:95]
	v_mfma_f32_16x16x32_bf16 v[96:99], v[164:167], v[28:31], v[96:99]
	ds_read_b128 v[164:167], v1 offset:47488
	ds_read_b128 v[196:199], v1 offset:47552
	s_waitcnt lgkmcnt(0)
	v_mfma_f32_16x16x32_bf16 v[100:103], v[164:167], v[12:15], v[100:103]
	v_mfma_f32_16x16x32_bf16 v[142:145], v[164:167], v[28:31], v[142:145]
	v_mfma_f32_16x16x32_bf16 v[164:167], v[168:171], v[16:19], v[68:71]
	v_mfma_f32_16x16x32_bf16 v[168:171], v[168:171], v[32:35], v[60:63]
	v_mfma_f32_16x16x32_bf16 v[200:203], v[172:175], v[16:19], v[64:67]
	s_nop 5
	v_fma_f32 v2, -v164, s50, v114
	v_fma_f32 v3, -v165, s50, v115
	v_pk_fma_f32 v[60:61], v[168:169], s[50:51], v[116:117] op_sel_hi:[1,0,1] neg_lo:[1,0,0] neg_hi:[1,0,0]
	v_min_f32_e32 v1, 0x42700000, v2
	v_min_f32_e32 v3, 0x42700000, v3
	v_min_f32_e32 v60, 0x42700000, v60
	v_min_f32_e32 v61, 0x42700000, v61
	v_exp_f32_e32 v2, v1
	v_exp_f32_e32 v3, v3
	v_exp_f32_e32 v64, v60
	v_exp_f32_e32 v65, v61
	v_mfma_f32_16x16x32_bf16 v[68:71], v[192:195], v[16:19], v[92:95]
	v_add_u32_e32 v1, s16, v126
	s_lshl_b32 s16, s34, 14
	s_xor_b32 s17, s16, 0x4000
	v_pk_add_f32 v[92:93], v[2:3], 1.0 op_sel_hi:[1,0]
	v_pk_add_f32 v[2:3], v[64:65], 1.0 op_sel_hi:[1,0]
	v_mfma_f32_16x16x32_bf16 v[172:175], v[172:175], v[32:35], v[84:87]
	v_mul_f32_e64 v64, v2, v92
	v_mul_f32_e64 v65, v3, v93
	v_pk_fma_f32 v[68:69], v[68:69], s[50:51], v[114:115] op_sel_hi:[1,0,1] neg_lo:[1,0,0] neg_hi:[1,0,0]
	v_rcp_f32_e32 v94, v64
	v_rcp_f32_e32 v95, v65
	v_mfma_f32_16x16x32_bf16 v[84:87], v[192:195], v[32:35], v[96:99]
	v_min_f32_e32 v68, 0x42700000, v68
	v_min_f32_e32 v69, 0x42700000, v69
	v_pk_mul_f32 v[2:3], v[2:3], v[94:95]
	v_mfma_f32_16x16x32_bf16 v[60:63], v[196:199], v[16:19], v[100:103]
	v_mul_f32_e64 v2, v118, v2
	v_mul_f32_e64 v3, v119, v3
	v_pk_fma_f32 v[98:99], v[166:167], s[50:51], v[114:115] op_sel_hi:[1,0,1] neg_lo:[1,0,0] neg_hi:[1,0,0]
	v_exp_f32_e32 v2, v2
	v_pk_fma_f32 v[100:101], v[170:171], s[50:51], v[116:117] op_sel_hi:[1,0,1] neg_lo:[1,0,0] neg_hi:[1,0,0]
	v_exp_f32_e32 v3, v3
	v_min_f32_e32 v98, 0x42700000, v98
	v_min_f32_e32 v99, 0x42700000, v99
	v_min_f32_e32 v100, 0x42700000, v100
	v_min_f32_e32 v101, 0x42700000, v101
	v_exp_f32_e32 v98, v98
	v_exp_f32_e32 v99, v99
	v_exp_f32_e32 v100, v100
	v_exp_f32_e32 v101, v101
	v_pk_mul_f32 v[92:93], v[92:93], v[94:95]
	v_pk_fma_f32 v[94:95], v[2:3], v[2:3], 1.0 op_sel_hi:[1,1,0] neg_lo:[1,0,0] neg_hi:[1,0,0]
	v_mfma_f32_16x16x32_bf16 v[64:67], v[196:199], v[32:35], v[142:145]
	ds_read_u16 v96, v1 offset:34304
	ds_read_u16 v97, v1 offset:34576
	ds_read_u16 v141, v1 offset:34848
	ds_read_u16 v144, v1 offset:35120
	ds_read_u16 v164, v1 offset:38656
	ds_read_u16 v165, v1 offset:38928
	ds_read_u16 v168, v1 offset:39200
	ds_read_u16 v169, v1 offset:39472
	v_max_f32_e32 v142, 0, v94
	v_max_f32_e32 v143, 0, v95
	v_pk_add_f32 v[94:95], v[98:99], 1.0 op_sel_hi:[1,0]
	v_pk_add_f32 v[98:99], v[100:101], 1.0 op_sel_hi:[1,0]
	s_waitcnt lgkmcnt(0)
; #define LAS __attribute__((address_space(3)))
; __device__ __forceinline__ float bf_1(bf16_t h) { return __uint_as_float(((unsigned)h) << 16); }
; template <int DIR>
; __device__ __forceinline__ void rnn_item(LAS unsigned char* lds, const bf16_t* proj, bf16_t* hout, int hpitch, int layer, int s, int n) {
;     ...
;         {   typedef float f32x2 __attribute__((ext_vector_type(2)));
; #pragma unroll
;             for (int mt = 0; mt < 4; ++mt)
; #pragma unroll
;                 for (int rp = 0; rp < 2; ++rp) {
;                     const LAS unsigned char* xp = At + buf * 17408 + (mt * 16 + kg * 4 + 2 * rp) * 272 + (w * 16 + l16) * 2;
;                     const f32x2 xc = {bf_1(*(const LAS bf16_t*)xp), bf_1(*(const LAS bf16_t*)(xp + 272))};
;                     const f32x2 xa = {aA[mt][2 * rp], aA[mt][2 * rp + 1]}, xx = {aX[mt][2 * rp], aX[mt][2 * rp + 1]};
;                     f32x2 ta = xa * (-LOG2E) + nba, tx = xx * (-LOG2E) + nbx;
;                     ta.x = fminf(ta.x, 60.f); ta.y = fminf(ta.y, 60.f); tx.x = fminf(tx.x, 60.f); tx.y = fminf(tx.y, 60.f);
;                     f32x2 ea, ex; ea.x = __builtin_amdgcn_exp2f(ta.x); ea.y = __builtin_amdgcn_exp2f(ta.y); ex.x = __builtin_amdgcn_exp2f(tx.x); ex.y = __builtin_amdgcn_exp2f(tx.y);
;                     const f32x2 da = ea + 1.0f, dx = ex + 1.0f, dd = da * dx;
;                     f32x2 inv; inv.x = __builtin_amdgcn_rcpf(dd.x); inv.y = __builtin_amdgcn_rcpf(dd.y);
;                     const f32x2 rr = dx * inv, ii = da * inv, tt = rr * clam2;
;                     f32x2 av; av.x = __builtin_amdgcn_exp2f(tt.x); av.y = __builtin_amdgcn_exp2f(tt.y);
;                     f32x2 om = 1.0f - av * av; om.x = fmaxf(om.x, 0.f); om.y = fmaxf(om.y, 0.f);
;                     f32x2 sq; sq.x = __builtin_amdgcn_sqrtf(om.x); sq.y = __builtin_amdgcn_sqrtf(om.y);
;                     const f32x2 bv = sq * (ii * xc);
;                     aA[mt][2 * rp] = av.x; aA[mt][2 * rp + 1] = av.y; aX[mt][2 * rp] = bv.x; aX[mt][2 * rp + 1] = bv.y;
;                 }
;         }
	v_lshlrev_b32_e32 v96, 16, v96
	v_pk_mul_f32 v[100:101], v[98:99], v[94:95]
	v_lshlrev_b32_e32 v97, 16, v97
	v_rcp_f32_e32 v102, v100
	v_rcp_f32_e32 v103, v101
	v_pk_mul_f32 v[92:93], v[92:93], v[96:97]
	v_sqrt_f32_e32 v142, v142
	v_sqrt_f32_e32 v143, v143
	v_pk_mul_f32 v[96:97], v[98:99], v[102:103]
	v_pk_mul_f32 v[94:95], v[94:95], v[102:103]
	v_pk_mul_f32 v[96:97], v[118:119], v[96:97]
	v_pk_mul_f32 v[92:93], v[92:93], v[142:143]
	v_exp_f32_e32 v100, v96
	v_exp_f32_e32 v101, v97
	v_lshlrev_b32_e32 v96, 16, v141
	v_pk_fma_f32 v[142:143], v[172:173], s[50:51], v[116:117] op_sel_hi:[1,0,1] neg_lo:[1,0,0] neg_hi:[1,0,0]
	v_lshlrev_b32_e32 v97, 16, v144
	v_pk_fma_f32 v[98:99], v[100:101], v[100:101], 1.0 op_sel_hi:[1,1,0] neg_lo:[1,0,0] neg_hi:[1,0,0]
	v_min_f32_e32 v142, 0x42700000, v142
	v_max_f32_e32 v141, 0, v98
	v_max_f32_e32 v145, 0, v99
	v_pk_fma_f32 v[98:99], v[200:201], s[50:51], v[114:115] op_sel_hi:[1,0,1] neg_lo:[1,0,0] neg_hi:[1,0,0]
	v_min_f32_e32 v143, 0x42700000, v143
	v_min_f32_e32 v98, 0x42700000, v98
	v_min_f32_e32 v99, 0x42700000, v99
	v_exp_f32_e32 v98, v98
	v_exp_f32_e32 v99, v99
	v_exp_f32_e32 v142, v142
	v_exp_f32_e32 v143, v143
	v_sqrt_f32_e32 v144, v141
	v_pk_add_f32 v[98:99], v[98:99], 1.0 op_sel_hi:[1,0]
	v_sqrt_f32_e32 v145, v145
	v_pk_add_f32 v[142:143], v[142:143], 1.0 op_sel_hi:[1,0]
	v_pk_mul_f32 v[94:95], v[94:95], v[96:97]
	v_pk_mul_f32 v[146:147], v[142:143], v[98:99]
	v_pk_mul_f32 v[96:97], v[94:95], v[144:145]
	v_rcp_f32_e32 v146, v146
	v_rcp_f32_e32 v147, v147
	v_pk_fma_f32 v[144:145], v[202:203], s[50:51], v[114:115] op_sel_hi:[1,0,1] neg_lo:[1,0,0] neg_hi:[1,0,0]
	v_pk_fma_f32 v[84:85], v[84:85], s[50:51], v[116:117] op_sel_hi:[1,0,1] neg_lo:[1,0,0] neg_hi:[1,0,0]
	v_min_f32_e32 v141, 0x42700000, v144
	v_pk_mul_f32 v[94:95], v[142:143], v[146:147]
	v_pk_mul_f32 v[98:99], v[98:99], v[146:147]
	v_pk_mul_f32 v[94:95], v[118:119], v[94:95]
	v_pk_fma_f32 v[146:147], v[174:175], s[50:51], v[116:117] op_sel_hi:[1,0,1] neg_lo:[1,0,0] neg_hi:[1,0,0]
	v_exp_f32_e32 v94, v94
	v_exp_f32_e32 v95, v95
	v_min_f32_e32 v145, 0x42700000, v145
	v_min_f32_e32 v146, 0x42700000, v146
	v_min_f32_e32 v147, 0x42700000, v147
	v_exp_f32_e32 v144, v141
	v_exp_f32_e32 v145, v145
	v_exp_f32_e32 v146, v146
	v_exp_f32_e32 v147, v147
	v_pk_fma_f32 v[142:143], v[94:95], v[94:95], 1.0 op_sel_hi:[1,1,0] neg_lo:[1,0,0] neg_hi:[1,0,0]
	v_min_f32_e32 v84, 0x42700000, v84
	v_min_f32_e32 v85, 0x42700000, v85
	v_lshlrev_b32_e32 v103, 16, v165
	v_max_f32_e32 v141, 0, v142
	v_max_f32_e32 v165, 0, v143
	v_pk_add_f32 v[142:143], v[144:145], 1.0 op_sel_hi:[1,0]
	v_pk_add_f32 v[144:145], v[146:147], 1.0 op_sel_hi:[1,0]
	v_exp_f32_e32 v68, v68
	v_exp_f32_e32 v69, v69
	v_exp_f32_e32 v84, v84
	v_exp_f32_e32 v85, v85
	v_pk_mul_f32 v[146:147], v[144:145], v[142:143]
	v_pk_add_f32 v[166:167], v[68:69], 1.0 op_sel_hi:[1,0]
	v_rcp_f32_e32 v146, v146
	v_rcp_f32_e32 v147, v147
	v_pk_add_f32 v[84:85], v[84:85], 1.0 op_sel_hi:[1,0]
	v_lshlrev_b32_e32 v102, 16, v164
	v_pk_mul_f32 v[68:69], v[84:85], v[166:167]
	v_pk_mul_f32 v[98:99], v[98:99], v[102:103]
	v_pk_mul_f32 v[102:103], v[144:145], v[146:147]
	v_lshlrev_b32_e32 v144, 16, v168
	v_lshlrev_b32_e32 v145, 16, v169
	v_rcp_f32_e32 v168, v68
	v_rcp_f32_e32 v169, v69
	v_pk_mul_f32 v[102:103], v[118:119], v[102:103]
	v_sqrt_f32_e32 v164, v141
	v_sqrt_f32_e32 v165, v165
	v_exp_f32_e32 v102, v102
	v_exp_f32_e32 v103, v103
	v_pk_mul_f32 v[84:85], v[84:85], v[168:169]
	v_pk_fma_f32 v[70:71], v[70:71], s[50:51], v[114:115] op_sel_hi:[1,0,1] neg_lo:[1,0,0] neg_hi:[1,0,0]
	v_pk_fma_f32 v[86:87], v[86:87], s[50:51], v[116:117] op_sel_hi:[1,0,1] neg_lo:[1,0,0] neg_hi:[1,0,0]
	v_pk_mul_f32 v[84:85], v[118:119], v[84:85]
	v_min_f32_e32 v70, 0x42700000, v70
	v_min_f32_e32 v71, 0x42700000, v71
	v_min_f32_e32 v86, 0x42700000, v86
	v_min_f32_e32 v87, 0x42700000, v87
	v_pk_mul_f32 v[98:99], v[98:99], v[164:165]
	v_pk_fma_f32 v[164:165], v[102:103], v[102:103], 1.0 op_sel_hi:[1,1,0] neg_lo:[1,0,0] neg_hi:[1,0,0]
	v_exp_f32_e32 v84, v84
	v_exp_f32_e32 v85, v85
	v_exp_f32_e32 v70, v70
	v_exp_f32_e32 v71, v71
	v_exp_f32_e32 v86, v86
	v_exp_f32_e32 v87, v87
	v_max_f32_e32 v141, 0, v164
	v_max_f32_e32 v165, 0, v165
	v_sqrt_f32_e32 v164, v141
	v_sqrt_f32_e32 v165, v165
	v_pk_mul_f32 v[68:69], v[142:143], v[146:147]
	ds_read_u16 v141, v1 offset:43008
	ds_read_u16 v143, v1 offset:43280
	ds_read_u16 v170, v1 offset:43552
	ds_read_u16 v171, v1 offset:43824
	ds_read_u16 v172, v1 offset:47360
	ds_read_u16 v173, v1 offset:47632
	ds_read_u16 v174, v1 offset:47904
	ds_read_u16 v1, v1 offset:48176
	v_pk_mul_f32 v[68:69], v[68:69], v[144:145]
	v_pk_fma_f32 v[144:145], v[84:85], v[84:85], 1.0 op_sel_hi:[1,1,0] neg_lo:[1,0,0] neg_hi:[1,0,0]
	v_pk_add_f32 v[146:147], v[70:71], 1.0 op_sel_hi:[1,0]
	v_pk_add_f32 v[86:87], v[86:87], 1.0 op_sel_hi:[1,0]
	v_pk_fma_f32 v[60:61], v[60:61], s[50:51], v[114:115] op_sel_hi:[1,0,1] neg_lo:[1,0,0] neg_hi:[1,0,0]
	v_pk_fma_f32 v[64:65], v[64:65], s[50:51], v[116:117] op_sel_hi:[1,0,1] neg_lo:[1,0,0] neg_hi:[1,0,0]
	s_waitcnt lgkmcnt(0)
; #define LAS __attribute__((address_space(3)))
; template <int DIR>
; __device__ __forceinline__ void rnn_item(LAS unsigned char* lds, const bf16_t* proj, bf16_t* hout, int hpitch, int layer, int s, int n) {
;     ...
;                     const LAS unsigned char* xp = At + buf * 17408 + (mt * 16 + kg * 4 + 2 * rp) * 272 + (w * 16 + l16) * 2;
;                     const f32x2 xc = {bf_1(*(const LAS bf16_t*)xp), bf_1(*(const LAS bf16_t*)(xp + 272))};
;                     const f32x2 xa = {aA[mt][2 * rp], aA[mt][2 * rp + 1]}, xx = {aX[mt][2 * rp], aX[mt][2 * rp + 1]};
;                     f32x2 ta = xa * (-LOG2E) + nba, tx = xx * (-LOG2E) + nbx;
;                     ta.x = fminf(ta.x, 60.f); ta.y = fminf(ta.y, 60.f); tx.x = fminf(tx.x, 60.f); tx.y = fminf(tx.y, 60.f);
;                     f32x2 ea, ex; ea.x = __builtin_amdgcn_exp2f(ta.x); ea.y = __builtin_amdgcn_exp2f(ta.y); ex.x = __builtin_amdgcn_exp2f(tx.x); ex.y = __builtin_amdgcn_exp2f(tx.y);
;                     const f32x2 da = ea + 1.0f, dx = ex + 1.0f, dd = da * dx;
;                     f32x2 inv; inv.x = __builtin_amdgcn_rcpf(dd.x); inv.y = __builtin_amdgcn_rcpf(dd.y);
;                     const f32x2 rr = dx * inv, ii = da * inv, tt = rr * clam2;
;                     f32x2 av; av.x = __builtin_amdgcn_exp2f(tt.x); av.y = __builtin_amdgcn_exp2f(tt.y);
;                     f32x2 om = 1.0f - av * av; om.x = fmaxf(om.x, 0.f); om.y = fmaxf(om.y, 0.f);
;                     f32x2 sq; sq.x = __builtin_amdgcn_sqrtf(om.x); sq.y = __builtin_amdgcn_sqrtf(om.y);
;                     const f32x2 bv = sq * (ii * xc);
;                     aA[mt][2 * rp] = av.x; aA[mt][2 * rp + 1] = av.y; aX[mt][2 * rp] = bv.x; aX[mt][2 * rp + 1] = bv.y;
;                 }
;         }
; #pragma unroll
;         for (int mt = 0; mt < 4; ++mt) {
;             float pp = 1.f, hh = 0.f;
; #pragma unroll
;             for (int q = 0; q < 4; ++q) { const int r = DIR == 0 ? q : 3 - q; hh = aA[mt][r] * hh + aX[mt][r]; pp *= aA[mt][r]; aA[mt][r] = pp; aX[mt][r] = hh; }
;         }
;         float start[4]; float carry = hcarry;
; #pragma unroll
;         for (int hq = 0; hq < 2; ++hq) {
;             float Ar[8], Br[8];
; #pragma unroll
;             for (int q8 = 0; q8 < 8; ++q8) { const int q = hq * 8 + q8; const int rho = DIR == 0 ? q : 15 - q; const int mt = rho >> 2, kgp = rho & 3; constexpr int re = DIR == 0 ? 3 : 0;
	v_lshlrev_b32_e32 v142, 16, v141
	v_max_f32_e32 v141, 0, v144
	v_max_f32_e32 v145, 0, v145
	v_pk_mul_f32 v[70:71], v[86:87], v[146:147]
	v_min_f32_e32 v60, 0x42700000, v60
	v_min_f32_e32 v61, 0x42700000, v61
	v_min_f32_e32 v64, 0x42700000, v64
	v_min_f32_e32 v65, 0x42700000, v65
	v_pk_mul_f32 v[68:69], v[68:69], v[164:165]
	v_sqrt_f32_e32 v144, v141
	v_sqrt_f32_e32 v145, v145
	v_rcp_f32_e32 v164, v70
	v_rcp_f32_e32 v165, v71
	v_exp_f32_e32 v60, v60
	v_exp_f32_e32 v61, v61
	v_exp_f32_e32 v64, v64
	v_exp_f32_e32 v65, v65
	v_lshlrev_b32_e32 v143, 16, v143
	v_pk_mul_f32 v[70:71], v[166:167], v[168:169]
	v_pk_fma_f32 v[62:63], v[62:63], s[50:51], v[114:115] op_sel_hi:[1,0,1] neg_lo:[1,0,0] neg_hi:[1,0,0]
	v_pk_mul_f32 v[70:71], v[70:71], v[142:143]
	v_pk_fma_f32 v[66:67], v[66:67], s[50:51], v[116:117] op_sel_hi:[1,0,1] neg_lo:[1,0,0] neg_hi:[1,0,0]
	v_pk_mul_f32 v[70:71], v[70:71], v[144:145]
	v_lshlrev_b32_e32 v142, 16, v170
	v_lshlrev_b32_e32 v143, 16, v171
	v_pk_mul_f32 v[144:145], v[146:147], v[164:165]
	v_pk_add_f32 v[60:61], v[60:61], 1.0 op_sel_hi:[1,0]
	v_pk_add_f32 v[64:65], v[64:65], 1.0 op_sel_hi:[1,0]
	v_min_f32_e32 v62, 0x42700000, v62
	v_min_f32_e32 v63, 0x42700000, v63
	v_min_f32_e32 v66, 0x42700000, v66
	v_min_f32_e32 v67, 0x42700000, v67
	v_pk_mul_f32 v[142:143], v[144:145], v[142:143]
	v_pk_mul_f32 v[144:145], v[64:65], v[60:61]
	v_exp_f32_e32 v62, v62
	v_exp_f32_e32 v63, v63
	v_exp_f32_e32 v66, v66
	v_exp_f32_e32 v67, v67
	v_rcp_f32_e32 v144, v144
	v_rcp_f32_e32 v145, v145
	v_pk_mul_f32 v[86:87], v[86:87], v[164:165]
	v_pk_add_f32 v[62:63], v[62:63], 1.0 op_sel_hi:[1,0]
	v_pk_mul_f32 v[86:87], v[118:119], v[86:87]
	v_pk_add_f32 v[66:67], v[66:67], 1.0 op_sel_hi:[1,0]
	v_exp_f32_e32 v86, v86
	v_exp_f32_e32 v87, v87
	v_pk_mul_f32 v[64:65], v[64:65], v[144:145]
	v_pk_mul_f32 v[164:165], v[66:67], v[62:63]
	v_pk_mul_f32 v[64:65], v[118:119], v[64:65]
	v_rcp_f32_e32 v164, v164
	v_rcp_f32_e32 v165, v165
	v_exp_f32_e32 v64, v64
	v_exp_f32_e32 v65, v65
	v_pk_fma_f32 v[146:147], v[86:87], v[86:87], 1.0 op_sel_hi:[1,1,0] neg_lo:[1,0,0] neg_hi:[1,0,0]
	v_pk_mul_f32 v[66:67], v[66:67], v[164:165]
	v_max_f32_e32 v141, 0, v146
	v_max_f32_e32 v147, 0, v147
	v_sqrt_f32_e32 v146, v141
	v_sqrt_f32_e32 v147, v147
	v_pk_mul_f32 v[60:61], v[60:61], v[144:145]
	v_pk_fma_f32 v[144:145], v[64:65], v[64:65], 1.0 op_sel_hi:[1,1,0] neg_lo:[1,0,0] neg_hi:[1,0,0]
	v_pk_mul_f32 v[66:67], v[118:119], v[66:67]
	v_max_f32_e32 v141, 0, v144
	v_max_f32_e32 v145, 0, v145
	v_exp_f32_e32 v66, v66
	v_exp_f32_e32 v67, v67
	v_sqrt_f32_e32 v144, v141
	v_sqrt_f32_e32 v145, v145
	v_pk_mul_f32 v[142:143], v[142:143], v[146:147]
	v_lshlrev_b32_e32 v146, 16, v172
	v_lshlrev_b32_e32 v147, 16, v173
	v_pk_mul_f32 v[60:61], v[60:61], v[146:147]
	v_pk_fma_f32 v[146:147], v[66:67], v[66:67], 1.0 op_sel_hi:[1,1,0] neg_lo:[1,0,0] neg_hi:[1,0,0]
	v_pk_mul_f32 v[144:145], v[60:61], v[144:145]
	v_max_f32_e32 v61, 0, v146
	v_max_f32_e32 v141, 0, v147
	v_sqrt_f32_e32 v146, v61
	v_sqrt_f32_e32 v147, v141
	v_lshlrev_b32_e32 v61, 16, v1
	v_fma_f32 v1, 0, v2, v92
	v_fmac_f32_e32 v93, v3, v1
	v_mul_f32_e32 v3, v2, v3
	v_lshlrev_b32_e32 v60, 16, v174
	v_pk_mul_f32 v[62:63], v[62:63], v[164:165]
	v_fma_f32 v92, v100, v93, v96
	v_mul_f32_e32 v96, v100, v3
	v_pk_mul_f32 v[60:61], v[62:63], v[60:61]
	v_fmac_f32_e32 v97, v101, v92
	v_mul_f32_e32 v100, v101, v96
	v_fma_f32 v98, 0, v94, v98
	v_pk_mul_f32 v[146:147], v[60:61], v[146:147]
	v_fmac_f32_e32 v99, v95, v98
	v_mul_f32_e32 v95, v94, v95
	v_fma_f32 v70, 0, v84, v70
	v_fma_f32 v141, 0, v64, v144
	ds_bpermute_b32 v60, v128, v100
	ds_bpermute_b32 v61, v128, v97
	v_fma_f32 v68, v102, v99, v68
	v_mul_f32_e32 v101, v102, v95
	v_fmac_f32_e32 v71, v85, v70
	v_fmac_f32_e32 v145, v65, v141
	ds_bpermute_b32 v62, v129, v100
	ds_bpermute_b32 v63, v129, v97
	v_fmac_f32_e32 v69, v103, v68
	v_mul_f32_e32 v102, v103, v101
	v_fma_f32 v103, v86, v71, v142
	v_fma_f32 v142, v66, v145, v146
	ds_bpermute_b32 v144, v130, v100
	ds_bpermute_b32 v146, v130, v97
	ds_bpermute_b32 v164, v131, v100
	ds_bpermute_b32 v165, v131, v97
	ds_bpermute_b32 v166, v128, v102
	ds_bpermute_b32 v167, v128, v69
	ds_bpermute_b32 v168, v129, v102
	ds_bpermute_b32 v169, v129, v69
	s_waitcnt lgkmcnt(0)
; #define LAS __attribute__((address_space(3)))
; __device__ __forceinline__ unsigned cvt_pk_bf16(float lo, float hi) { unsigned r; asm volatile("v_cvt_pk_bf16_f32 %0, %1, %2" : "=v"(r) : "v"(lo), "v"(hi)); return r; }
; #define RNN_BAR() do { asm volatile("s_waitcnt lgkmcnt(0)" ::: "memory"); __builtin_amdgcn_s_barrier(); asm volatile("" ::: "memory"); } while (0)
; template <int DIR>
; __device__ __forceinline__ void rnn_item(LAS unsigned char* lds, const bf16_t* proj, bf16_t* hout, int hpitch, int layer, int s, int n) {
;     ...
;             for (int q8 = 0; q8 < 8; ++q8) { const int q = hq * 8 + q8; const int rho = DIR == 0 ? q : 15 - q; const int mt = rho >> 2, kgp = rho & 3; constexpr int re = DIR == 0 ? 3 : 0;
;                 Ar[q8] = __shfl(aA[mt][re], l16 + 16 * kgp); Br[q8] = __shfl(aX[mt][re], l16 + 16 * kgp); }
; #pragma unroll
;             for (int q8 = 0; q8 < 8; ++q8) { const int q = hq * 8 + q8; const int rho = DIR == 0 ? q : 15 - q; const int mt = rho >> 2, kgp = rho & 3;
;                 if (kg == kgp) start[mt] = carry;
;                 carry = Ar[q8] * carry + Br[q8]; }
;         }
;         hcarry = carry;
;         if (it > 0) {
; #pragma unroll
;             for (int i = 0; i < 2; ++i) { const int c = tid + 512 * i; const u32x4 v = *(const LAS u32x4*)(OUTB + (buf ^ 1) * 16384 + c * 16);
;                 *(u32x4*)(hout + (seqbase + (size_t)(sub - stp) * 64 + (c >> 4)) * hpitch + n * 128 + (c & 15) * 8) = v; }
;         }
;         {   LAS unsigned short* ob = (LAS unsigned short*)(OUTB + buf * 16384 + (kg * 4) * 256 + (w * 16 + l16) * 2);
; #pragma unroll
;             for (int mt = 0; mt < 4; ++mt)
; #pragma unroll
;                 for (int rp = 0; rp < 2; ++rp) {
;                     const float h0 = aX[mt][2 * rp] + aA[mt][2 * rp] * start[mt], h1 = aX[mt][2 * rp + 1] + aA[mt][2 * rp + 1] * start[mt];
;                     const unsigned pk = cvt_pk_bf16(h0, h1);
;                     ob[(mt * 16 + 2 * rp) * 128] = (unsigned short)(pk & 0xffffu); ob[(mt * 16 + 2 * rp + 1) * 128] = (unsigned short)(pk >> 16);
;                 }
;         }
;         RNN_BAR();
	v_fmac_f32_e32 v61, v136, v60
	ds_bpermute_b32 v170, v130, v102
	ds_bpermute_b32 v171, v130, v69
	v_fmac_f32_e32 v63, v61, v62
	v_cndmask_b32_e64 v60, v132, v61, s[8:9]
	v_fmac_f32_e32 v146, v63, v144
	v_cndmask_b32_e64 v60, v60, v63, s[10:11]
	v_fmac_f32_e32 v165, v146, v164
	v_mul_f32_e32 v85, v84, v85
	v_cndmask_b32_e64 v132, v60, v146, s[12:13]
	v_cndmask_b32_e64 v60, v133, v165, s[6:7]
	v_fmac_f32_e32 v167, v165, v166
	v_mul_f32_e32 v86, v86, v85
	v_cndmask_b32_e64 v60, v60, v167, s[8:9]
	v_fmac_f32_e32 v169, v167, v168
	v_fmac_f32_e32 v143, v87, v103
	v_mul_f32_e32 v87, v87, v86
	ds_bpermute_b32 v172, v131, v102
	ds_bpermute_b32 v173, v131, v69
	v_cndmask_b32_e64 v60, v60, v169, s[10:11]
	s_waitcnt lgkmcnt(0)
	v_fmac_f32_e32 v171, v169, v170
	v_cndmask_b32_e64 v133, v60, v171, s[12:13]
	ds_bpermute_b32 v60, v128, v87
	ds_bpermute_b32 v61, v128, v143
	ds_bpermute_b32 v62, v129, v87
	ds_bpermute_b32 v63, v129, v143
	ds_bpermute_b32 v144, v130, v87
	ds_bpermute_b32 v146, v130, v143
	v_fmac_f32_e32 v173, v171, v172
	v_cndmask_b32_e64 v134, v134, v173, s[6:7]
	s_waitcnt lgkmcnt(0)
	v_fmac_f32_e32 v61, v173, v60
	v_cndmask_b32_e64 v60, v134, v61, s[8:9]
	v_fmac_f32_e32 v63, v61, v62
	s_add_i32 s17, s17, 0
	v_cndmask_b32_e64 v60, v60, v63, s[10:11]
	v_fmac_f32_e32 v146, v63, v144
	s_add_i32 s17, s17, 0x11800
	v_cndmask_b32_e64 v134, v60, v146, s[12:13]
	v_add_u32_e32 v60, s17, v113
	ds_read_b128 v[60:63], v60
	v_mul_f32_e32 v65, v64, v65
	v_mul_f32_e32 v66, v66, v65
	v_fmac_f32_e32 v147, v67, v142
	v_mul_f32_e32 v67, v67, v66
	s_waitcnt lgkmcnt(0)
	global_store_dwordx4 v[90:91], v[60:63], off
	ds_bpermute_b32 v164, v131, v87
	ds_bpermute_b32 v165, v131, v143
	v_add_u32_e32 v60, s17, v121
	ds_read_b128 v[60:63], v60
	ds_bpermute_b32 v166, v128, v67
	ds_bpermute_b32 v167, v128, v147
	ds_bpermute_b32 v168, v129, v67
	ds_bpermute_b32 v169, v129, v147
	ds_bpermute_b32 v170, v130, v67
	ds_bpermute_b32 v171, v130, v147
	v_fmac_f32_e32 v1, v2, v132
	s_waitcnt lgkmcnt(0)
	global_store_dwordx4 v[88:89], v[60:63], off
	v_fmac_f32_e32 v93, v3, v132
	v_cvt_pk_bf16_f32 v1, v1, v93
	v_fmac_f32_e32 v165, v146, v164
	v_add_u32_e32 v60, s16, v124
	ds_write_b16 v60, v1
	ds_write_b16_d16_hi v60, v1 offset:256
	v_fmac_f32_e32 v92, v96, v132
	v_fmac_f32_e32 v97, v100, v132
	v_cvt_pk_bf16_f32 v1, v92, v97
	v_cndmask_b32_e64 v135, v135, v165, s[6:7]
	v_fmac_f32_e32 v167, v165, v166
	ds_write_b16 v60, v1 offset:512
	ds_write_b16_d16_hi v60, v1 offset:768
	v_fmac_f32_e32 v98, v94, v133
	v_fmac_f32_e32 v99, v95, v133
	v_cvt_pk_bf16_f32 v1, v98, v99
	v_cndmask_b32_e64 v135, v135, v167, s[8:9]
	v_fmac_f32_e32 v169, v167, v168
	ds_write_b16 v60, v1 offset:4096
	ds_write_b16_d16_hi v60, v1 offset:4352
	v_fmac_f32_e32 v68, v101, v133
	v_fmac_f32_e32 v69, v102, v133
	v_cvt_pk_bf16_f32 v1, v68, v69
	v_cndmask_b32_e64 v135, v135, v169, s[10:11]
	v_fmac_f32_e32 v171, v169, v170
	ds_write_b16 v60, v1 offset:4608
	ds_write_b16_d16_hi v60, v1 offset:4864
	v_fmac_f32_e32 v70, v84, v134
	v_fmac_f32_e32 v71, v85, v134
	v_cvt_pk_bf16_f32 v1, v70, v71
	v_cndmask_b32_e64 v135, v135, v171, s[12:13]
	ds_write_b16 v60, v1 offset:8192
	ds_write_b16_d16_hi v60, v1 offset:8448
	v_fmac_f32_e32 v103, v86, v134
	v_fmac_f32_e32 v143, v87, v134
	v_cvt_pk_bf16_f32 v1, v103, v143
	ds_bpermute_b32 v172, v131, v67
	ds_bpermute_b32 v136, v131, v147
	ds_write_b16 v60, v1 offset:8704
	ds_write_b16_d16_hi v60, v1 offset:8960
	v_fmac_f32_e32 v141, v64, v135
	v_fmac_f32_e32 v145, v65, v135
	v_cvt_pk_bf16_f32 v1, v141, v145
	ds_write_b16 v60, v1 offset:12288
	ds_write_b16_d16_hi v60, v1 offset:12544
	v_fmac_f32_e32 v142, v66, v135
	v_fmac_f32_e32 v147, v67, v135
	v_cvt_pk_bf16_f32 v1, v142, v147
	ds_write_b16 v60, v1 offset:12800
	ds_write_b16_d16_hi v60, v1 offset:13056
	s_waitcnt lgkmcnt(0)
	s_barrier
	s_mov_b64 s[16:17], 0x70000
	s_waitcnt lgkmcnt(0)
	v_fmac_f32_e32 v136, v171, v172
	v_lshl_add_u64 v[88:89], v[88:89], 0, s[16:17]
	v_lshl_add_u64 v[90:91], v[90:91], 0, s[16:17]
	s_cmp_lg_u32 s19, 0x1bc8000
	s_cbranch_scc0 .LBB0_626
